# GEMM tile loops: per-tile accumulator clear with 63 v_mov_b64 instead of 126 v_mov_b32
# baseline (speedup 1.0000x reference)
.LBB0_210:
	s_ashr_i32 s13, s12, 31
	s_lshl_b64 s[14:15], s[12:13], 20
	s_add_u32 s14, s6, s14
	s_addc_u32 s15, s7, s15
	s_and_b64 s[16:17], s[2:3], exec
	s_cselect_b32 s13, s15, s47
	s_cselect_b32 s75, s14, s46
	s_ashr_i32 s11, s10, 31
	s_lshl_b64 s[16:17], s[10:11], 20
	s_add_u32 s16, s18, s16
	s_addc_u32 s17, s19, s17
	s_and_b64 s[56:57], s[2:3], exec
	s_cselect_b32 s11, s17, s49
	s_cselect_b32 s76, s16, s48
	s_add_u32 s77, s48, 0x100
	v_mov_b32_e32 v0, 0
	s_addc_u32 s78, s49, 0
	s_mov_b32 s79, -2
	v_mov_b32_e32 v1, v0
	v_mov_b64_e32 v[2:3], v[0:1]
	v_mov_b64_e32 v[4:5], v[0:1]
	v_mov_b64_e32 v[6:7], v[0:1]
	v_mov_b64_e32 v[8:9], v[0:1]
	v_mov_b64_e32 v[10:11], v[0:1]
	v_mov_b64_e32 v[16:17], v[0:1]
	v_mov_b64_e32 v[18:19], v[0:1]
	v_mov_b64_e32 v[24:25], v[0:1]
	v_mov_b64_e32 v[26:27], v[0:1]
	v_mov_b64_e32 v[32:33], v[0:1]
	v_mov_b64_e32 v[34:35], v[0:1]
	v_mov_b64_e32 v[40:41], v[0:1]
	v_mov_b64_e32 v[42:43], v[0:1]
	v_mov_b64_e32 v[48:49], v[0:1]
	v_mov_b64_e32 v[50:51], v[0:1]
	v_mov_b64_e32 v[12:13], v[0:1]
	v_mov_b64_e32 v[14:15], v[0:1]
	v_mov_b64_e32 v[20:21], v[0:1]
	v_mov_b64_e32 v[22:23], v[0:1]
	v_mov_b64_e32 v[28:29], v[0:1]
	v_mov_b64_e32 v[30:31], v[0:1]
	v_mov_b64_e32 v[36:37], v[0:1]
	v_mov_b64_e32 v[38:39], v[0:1]
	v_mov_b64_e32 v[44:45], v[0:1]
	v_mov_b64_e32 v[46:47], v[0:1]
	v_mov_b64_e32 v[52:53], v[0:1]
	v_mov_b64_e32 v[54:55], v[0:1]
	v_mov_b64_e32 v[56:57], v[0:1]
	v_mov_b64_e32 v[58:59], v[0:1]
	v_mov_b64_e32 v[60:61], v[0:1]
	v_mov_b64_e32 v[62:63], v[0:1]
	v_mov_b64_e32 v[64:65], v[0:1]
	v_mov_b64_e32 v[66:67], v[0:1]
	v_mov_b64_e32 v[68:69], v[0:1]
	v_mov_b64_e32 v[70:71], v[0:1]
	v_mov_b64_e32 v[72:73], v[0:1]
	v_mov_b64_e32 v[74:75], v[0:1]
	v_mov_b64_e32 v[80:81], v[0:1]
	v_mov_b64_e32 v[82:83], v[0:1]
	v_mov_b64_e32 v[88:89], v[0:1]
	v_mov_b64_e32 v[90:91], v[0:1]
	v_mov_b64_e32 v[96:97], v[0:1]
	v_mov_b64_e32 v[98:99], v[0:1]
	v_mov_b64_e32 v[108:109], v[0:1]
	v_mov_b64_e32 v[110:111], v[0:1]
	v_mov_b64_e32 v[116:117], v[0:1]
	v_mov_b64_e32 v[118:119], v[0:1]
	v_mov_b64_e32 v[76:77], v[0:1]
	v_mov_b64_e32 v[78:79], v[0:1]
	v_mov_b64_e32 v[84:85], v[0:1]
	v_mov_b64_e32 v[86:87], v[0:1]
	v_mov_b64_e32 v[92:93], v[0:1]
	v_mov_b64_e32 v[94:95], v[0:1]
	v_mov_b64_e32 v[100:101], v[0:1]
	v_mov_b64_e32 v[102:103], v[0:1]
	v_mov_b64_e32 v[104:105], v[0:1]
	v_mov_b64_e32 v[106:107], v[0:1]
	v_mov_b64_e32 v[112:113], v[0:1]
	v_mov_b64_e32 v[114:115], v[0:1]
	v_mov_b64_e32 v[120:121], v[0:1]
	v_mov_b64_e32 v[122:123], v[0:1]
	v_mov_b64_e32 v[124:125], v[0:1]
	v_mov_b64_e32 v[126:127], v[0:1]

.LBB0_639:
	s_ashr_i32 s49, s48, 31
	s_lshl_b64 s[54:55], s[48:49], 20
	s_add_u32 s54, s2, s54
	s_addc_u32 s55, s3, s55
	s_and_b64 s[56:57], s[8:9], exec
	s_cselect_b32 s49, s55, s63
	s_cselect_b32 s59, s54, s62
	s_ashr_i32 s47, s46, 31
	s_lshl_b64 s[56:57], s[46:47], 20
	s_add_u32 s56, s18, s56
	s_addc_u32 s57, s19, s57
	s_and_b64 s[66:67], s[8:9], exec
	s_cselect_b32 s47, s57, s65
	s_cselect_b32 s75, s56, s64
	s_add_u32 s76, s64, 0x100
	v_mov_b32_e32 v0, 0
	s_addc_u32 s77, s65, 0
	s_mov_b32 s78, -2
	s_waitcnt lgkmcnt(0)
	v_mov_b32_e32 v1, v0
	v_mov_b64_e32 v[2:3], v[0:1]
	v_mov_b64_e32 v[4:5], v[0:1]
	v_mov_b64_e32 v[6:7], v[0:1]
	v_mov_b64_e32 v[16:17], v[0:1]
	v_mov_b64_e32 v[18:19], v[0:1]
	v_mov_b64_e32 v[20:21], v[0:1]
	v_mov_b64_e32 v[22:23], v[0:1]
	v_mov_b64_e32 v[32:33], v[0:1]
	v_mov_b64_e32 v[34:35], v[0:1]
	v_mov_b64_e32 v[36:37], v[0:1]
	v_mov_b64_e32 v[38:39], v[0:1]
	v_mov_b64_e32 v[48:49], v[0:1]
	v_mov_b64_e32 v[50:51], v[0:1]
	v_mov_b64_e32 v[52:53], v[0:1]
	v_mov_b64_e32 v[54:55], v[0:1]
	v_mov_b64_e32 v[8:9], v[0:1]
	v_mov_b64_e32 v[10:11], v[0:1]
	v_mov_b64_e32 v[12:13], v[0:1]
	v_mov_b64_e32 v[14:15], v[0:1]
	v_mov_b64_e32 v[24:25], v[0:1]
	v_mov_b64_e32 v[26:27], v[0:1]
	v_mov_b64_e32 v[28:29], v[0:1]
	v_mov_b64_e32 v[30:31], v[0:1]
	v_mov_b64_e32 v[40:41], v[0:1]
	v_mov_b64_e32 v[42:43], v[0:1]
	v_mov_b64_e32 v[44:45], v[0:1]
	v_mov_b64_e32 v[46:47], v[0:1]
	v_mov_b64_e32 v[56:57], v[0:1]
	v_mov_b64_e32 v[58:59], v[0:1]
	v_mov_b64_e32 v[60:61], v[0:1]
	v_mov_b64_e32 v[62:63], v[0:1]
	v_mov_b64_e32 v[64:65], v[0:1]
	v_mov_b64_e32 v[66:67], v[0:1]
	v_mov_b64_e32 v[68:69], v[0:1]
	v_mov_b64_e32 v[70:71], v[0:1]
	v_mov_b64_e32 v[80:81], v[0:1]
	v_mov_b64_e32 v[82:83], v[0:1]
	v_mov_b64_e32 v[84:85], v[0:1]
	v_mov_b64_e32 v[86:87], v[0:1]
	v_mov_b64_e32 v[96:97], v[0:1]
	v_mov_b64_e32 v[98:99], v[0:1]
	v_mov_b64_e32 v[100:101], v[0:1]
	v_mov_b64_e32 v[102:103], v[0:1]
	v_mov_b64_e32 v[112:113], v[0:1]
	v_mov_b64_e32 v[114:115], v[0:1]
	v_mov_b64_e32 v[116:117], v[0:1]
	v_mov_b64_e32 v[118:119], v[0:1]
	v_mov_b64_e32 v[72:73], v[0:1]
	v_mov_b64_e32 v[74:75], v[0:1]
	v_mov_b64_e32 v[76:77], v[0:1]
	v_mov_b64_e32 v[78:79], v[0:1]
	v_mov_b64_e32 v[88:89], v[0:1]
	v_mov_b64_e32 v[90:91], v[0:1]
	v_mov_b64_e32 v[92:93], v[0:1]
	v_mov_b64_e32 v[94:95], v[0:1]
	v_mov_b64_e32 v[104:105], v[0:1]
	v_mov_b64_e32 v[106:107], v[0:1]
	v_mov_b64_e32 v[108:109], v[0:1]
	v_mov_b64_e32 v[110:111], v[0:1]
	v_mov_b64_e32 v[120:121], v[0:1]
	v_mov_b64_e32 v[122:123], v[0:1]
	v_mov_b64_e32 v[124:125], v[0:1]
	v_mov_b64_e32 v[126:127], v[0:1]

.LBB0_731:
	s_ashr_i32 s49, s48, 31
	s_lshl_b64 s[44:45], s[48:49], 20
	s_add_u32 s52, s3, s44
	s_addc_u32 s53, s18, s45
	s_and_b64 s[44:45], s[6:7], exec
	s_cselect_b32 s44, s53, s57
	s_cselect_b32 s45, s52, s56
	s_ashr_i32 s47, s46, 31
	s_lshl_b64 s[54:55], s[46:47], 20
	s_add_u32 s54, s19, s54
	s_addc_u32 s55, s21, s55
	s_and_b64 s[60:61], s[6:7], exec
	s_cselect_b32 s47, s55, s59
	s_cselect_b32 s49, s54, s58
	s_add_u32 s71, s58, 0x100
	v_mov_b32_e32 v0, 0
	s_addc_u32 s72, s59, 0
	s_mov_b32 s73, -2
	v_mov_b32_e32 v1, v0
	v_mov_b64_e32 v[2:3], v[0:1]
	v_mov_b64_e32 v[4:5], v[0:1]
	v_mov_b64_e32 v[6:7], v[0:1]
	v_mov_b64_e32 v[16:17], v[0:1]
	v_mov_b64_e32 v[18:19], v[0:1]
	v_mov_b64_e32 v[20:21], v[0:1]
	v_mov_b64_e32 v[22:23], v[0:1]
	v_mov_b64_e32 v[32:33], v[0:1]
	v_mov_b64_e32 v[34:35], v[0:1]
	v_mov_b64_e32 v[36:37], v[0:1]
	v_mov_b64_e32 v[38:39], v[0:1]
	v_mov_b64_e32 v[48:49], v[0:1]
	v_mov_b64_e32 v[50:51], v[0:1]
	v_mov_b64_e32 v[52:53], v[0:1]
	v_mov_b64_e32 v[54:55], v[0:1]
	v_mov_b64_e32 v[8:9], v[0:1]
	v_mov_b64_e32 v[10:11], v[0:1]
	v_mov_b64_e32 v[12:13], v[0:1]
	v_mov_b64_e32 v[14:15], v[0:1]
	v_mov_b64_e32 v[24:25], v[0:1]
	v_mov_b64_e32 v[26:27], v[0:1]
	v_mov_b64_e32 v[28:29], v[0:1]
	v_mov_b64_e32 v[30:31], v[0:1]
	v_mov_b64_e32 v[40:41], v[0:1]
	v_mov_b64_e32 v[42:43], v[0:1]
	v_mov_b64_e32 v[44:45], v[0:1]
	v_mov_b64_e32 v[46:47], v[0:1]
	v_mov_b64_e32 v[56:57], v[0:1]
	v_mov_b64_e32 v[58:59], v[0:1]
	v_mov_b64_e32 v[60:61], v[0:1]
	v_mov_b64_e32 v[62:63], v[0:1]
	v_mov_b64_e32 v[64:65], v[0:1]
	v_mov_b64_e32 v[66:67], v[0:1]
	v_mov_b64_e32 v[68:69], v[0:1]
	v_mov_b64_e32 v[70:71], v[0:1]
	v_mov_b64_e32 v[80:81], v[0:1]
	v_mov_b64_e32 v[82:83], v[0:1]
	v_mov_b64_e32 v[84:85], v[0:1]
	v_mov_b64_e32 v[86:87], v[0:1]
	v_mov_b64_e32 v[96:97], v[0:1]
	v_mov_b64_e32 v[98:99], v[0:1]
	v_mov_b64_e32 v[100:101], v[0:1]
	v_mov_b64_e32 v[102:103], v[0:1]
	v_mov_b64_e32 v[112:113], v[0:1]
	v_mov_b64_e32 v[114:115], v[0:1]
	v_mov_b64_e32 v[116:117], v[0:1]
	v_mov_b64_e32 v[118:119], v[0:1]
	v_mov_b64_e32 v[72:73], v[0:1]
	v_mov_b64_e32 v[74:75], v[0:1]
	v_mov_b64_e32 v[76:77], v[0:1]
	v_mov_b64_e32 v[78:79], v[0:1]
	v_mov_b64_e32 v[88:89], v[0:1]
	v_mov_b64_e32 v[90:91], v[0:1]
	v_mov_b64_e32 v[92:93], v[0:1]
	v_mov_b64_e32 v[94:95], v[0:1]
	v_mov_b64_e32 v[104:105], v[0:1]
	v_mov_b64_e32 v[106:107], v[0:1]
	v_mov_b64_e32 v[108:109], v[0:1]
	v_mov_b64_e32 v[110:111], v[0:1]
	v_mov_b64_e32 v[120:121], v[0:1]
	v_mov_b64_e32 v[122:123], v[0:1]
	v_mov_b64_e32 v[124:125], v[0:1]
	v_mov_b64_e32 v[126:127], v[0:1]

.LBB0_809:
	s_ashr_i32 s55, s54, 31
	s_lshl_b64 s[56:57], s[54:55], 22
	s_add_u32 s56, s2, s56
	s_addc_u32 s57, s3, s57
	s_and_b64 s[58:59], s[8:9], exec
	s_cselect_b32 s55, s57, s65
	s_cselect_b32 s61, s56, s64
	s_ashr_i32 s53, s52, 31
	s_lshl_b64 s[58:59], s[52:53], 22
	s_add_u32 s58, s18, s58
	s_addc_u32 s59, s19, s59
	s_and_b64 s[70:71], s[8:9], exec
	s_cselect_b32 s53, s59, s67
	s_cselect_b32 s75, s58, s66
	s_add_u32 s76, s66, 0x100
	v_mov_b32_e32 v0, 0
	s_addc_u32 s77, s67, 0
	s_mov_b32 s78, -2
	s_waitcnt lgkmcnt(0)
	v_mov_b32_e32 v1, v0
	v_mov_b64_e32 v[2:3], v[0:1]
	v_mov_b64_e32 v[4:5], v[0:1]
	v_mov_b64_e32 v[6:7], v[0:1]
	v_mov_b64_e32 v[16:17], v[0:1]
	v_mov_b64_e32 v[18:19], v[0:1]
	v_mov_b64_e32 v[20:21], v[0:1]
	v_mov_b64_e32 v[22:23], v[0:1]
	v_mov_b64_e32 v[32:33], v[0:1]
	v_mov_b64_e32 v[34:35], v[0:1]
	v_mov_b64_e32 v[36:37], v[0:1]
	v_mov_b64_e32 v[38:39], v[0:1]
	v_mov_b64_e32 v[48:49], v[0:1]
	v_mov_b64_e32 v[50:51], v[0:1]
	v_mov_b64_e32 v[52:53], v[0:1]
	v_mov_b64_e32 v[54:55], v[0:1]
	v_mov_b64_e32 v[8:9], v[0:1]
	v_mov_b64_e32 v[10:11], v[0:1]
	v_mov_b64_e32 v[12:13], v[0:1]
	v_mov_b64_e32 v[14:15], v[0:1]
	v_mov_b64_e32 v[24:25], v[0:1]
	v_mov_b64_e32 v[26:27], v[0:1]
	v_mov_b64_e32 v[28:29], v[0:1]
	v_mov_b64_e32 v[30:31], v[0:1]
	v_mov_b64_e32 v[40:41], v[0:1]
	v_mov_b64_e32 v[42:43], v[0:1]
	v_mov_b64_e32 v[44:45], v[0:1]
	v_mov_b64_e32 v[46:47], v[0:1]
	v_mov_b64_e32 v[56:57], v[0:1]
	v_mov_b64_e32 v[58:59], v[0:1]
	v_mov_b64_e32 v[60:61], v[0:1]
	v_mov_b64_e32 v[62:63], v[0:1]
	v_mov_b64_e32 v[64:65], v[0:1]
	v_mov_b64_e32 v[66:67], v[0:1]
	v_mov_b64_e32 v[68:69], v[0:1]
	v_mov_b64_e32 v[70:71], v[0:1]
	v_mov_b64_e32 v[80:81], v[0:1]
	v_mov_b64_e32 v[82:83], v[0:1]
	v_mov_b64_e32 v[84:85], v[0:1]
	v_mov_b64_e32 v[86:87], v[0:1]
	v_mov_b64_e32 v[96:97], v[0:1]
	v_mov_b64_e32 v[98:99], v[0:1]
	v_mov_b64_e32 v[100:101], v[0:1]
	v_mov_b64_e32 v[102:103], v[0:1]
	v_mov_b64_e32 v[112:113], v[0:1]
	v_mov_b64_e32 v[114:115], v[0:1]
	v_mov_b64_e32 v[116:117], v[0:1]
	v_mov_b64_e32 v[118:119], v[0:1]
	v_mov_b64_e32 v[72:73], v[0:1]
	v_mov_b64_e32 v[74:75], v[0:1]
	v_mov_b64_e32 v[76:77], v[0:1]
	v_mov_b64_e32 v[78:79], v[0:1]
	v_mov_b64_e32 v[88:89], v[0:1]
	v_mov_b64_e32 v[90:91], v[0:1]
	v_mov_b64_e32 v[92:93], v[0:1]
	v_mov_b64_e32 v[94:95], v[0:1]
	v_mov_b64_e32 v[104:105], v[0:1]
	v_mov_b64_e32 v[106:107], v[0:1]
	v_mov_b64_e32 v[108:109], v[0:1]
	v_mov_b64_e32 v[110:111], v[0:1]
	v_mov_b64_e32 v[120:121], v[0:1]
	v_mov_b64_e32 v[122:123], v[0:1]
	v_mov_b64_e32 v[124:125], v[0:1]
	v_mov_b64_e32 v[126:127], v[0:1]

.LBB0_895:
	s_ashr_i32 s53, s52, 31
	s_lshl_b64 s[44:45], s[52:53], 20
	s_add_u32 s54, s2, s44
	s_addc_u32 s55, s3, s45
	s_and_b64 s[44:45], s[6:7], exec
	s_cselect_b32 s1, s55, s59
	s_cselect_b32 s9, s54, s58
	s_ashr_i32 s49, s48, 31
	s_lshl_b64 s[44:45], s[48:49], 20
	s_add_u32 s56, s18, s44
	s_addc_u32 s57, s19, s45
	s_and_b64 s[44:45], s[6:7], exec
	s_cselect_b32 s44, s57, s61
	s_cselect_b32 s45, s56, s60
	s_add_u32 s49, s60, 0x100
	v_mov_b32_e32 v0, 0
	s_addc_u32 s53, s61, 0
	s_mov_b32 s75, -2
	v_mov_b32_e32 v1, v0
	v_mov_b64_e32 v[2:3], v[0:1]
	v_mov_b64_e32 v[4:5], v[0:1]
	v_mov_b64_e32 v[6:7], v[0:1]
	v_mov_b64_e32 v[16:17], v[0:1]
	v_mov_b64_e32 v[18:19], v[0:1]
	v_mov_b64_e32 v[20:21], v[0:1]
	v_mov_b64_e32 v[22:23], v[0:1]
	v_mov_b64_e32 v[32:33], v[0:1]
	v_mov_b64_e32 v[34:35], v[0:1]
	v_mov_b64_e32 v[36:37], v[0:1]
	v_mov_b64_e32 v[38:39], v[0:1]
	v_mov_b64_e32 v[48:49], v[0:1]
	v_mov_b64_e32 v[50:51], v[0:1]
	v_mov_b64_e32 v[52:53], v[0:1]
	v_mov_b64_e32 v[54:55], v[0:1]
	v_mov_b64_e32 v[8:9], v[0:1]
	v_mov_b64_e32 v[10:11], v[0:1]
	v_mov_b64_e32 v[12:13], v[0:1]
	v_mov_b64_e32 v[14:15], v[0:1]
	v_mov_b64_e32 v[24:25], v[0:1]
	v_mov_b64_e32 v[26:27], v[0:1]
	v_mov_b64_e32 v[28:29], v[0:1]
	v_mov_b64_e32 v[30:31], v[0:1]
	v_mov_b64_e32 v[40:41], v[0:1]
	v_mov_b64_e32 v[42:43], v[0:1]
	v_mov_b64_e32 v[44:45], v[0:1]
	v_mov_b64_e32 v[46:47], v[0:1]
	v_mov_b64_e32 v[56:57], v[0:1]
	v_mov_b64_e32 v[58:59], v[0:1]
	v_mov_b64_e32 v[60:61], v[0:1]
	v_mov_b64_e32 v[62:63], v[0:1]
	v_mov_b64_e32 v[64:65], v[0:1]
	v_mov_b64_e32 v[66:67], v[0:1]
	v_mov_b64_e32 v[68:69], v[0:1]
	v_mov_b64_e32 v[70:71], v[0:1]
	v_mov_b64_e32 v[80:81], v[0:1]
	v_mov_b64_e32 v[82:83], v[0:1]
	v_mov_b64_e32 v[84:85], v[0:1]
	v_mov_b64_e32 v[86:87], v[0:1]
	v_mov_b64_e32 v[96:97], v[0:1]
	v_mov_b64_e32 v[98:99], v[0:1]
	v_mov_b64_e32 v[100:101], v[0:1]
	v_mov_b64_e32 v[102:103], v[0:1]
	v_mov_b64_e32 v[112:113], v[0:1]
	v_mov_b64_e32 v[114:115], v[0:1]
	v_mov_b64_e32 v[116:117], v[0:1]
	v_mov_b64_e32 v[118:119], v[0:1]
	v_mov_b64_e32 v[72:73], v[0:1]
	v_mov_b64_e32 v[74:75], v[0:1]
	v_mov_b64_e32 v[76:77], v[0:1]
	v_mov_b64_e32 v[78:79], v[0:1]
	v_mov_b64_e32 v[88:89], v[0:1]
	v_mov_b64_e32 v[90:91], v[0:1]
	v_mov_b64_e32 v[92:93], v[0:1]
	v_mov_b64_e32 v[94:95], v[0:1]
	v_mov_b64_e32 v[104:105], v[0:1]
	v_mov_b64_e32 v[106:107], v[0:1]
	v_mov_b64_e32 v[108:109], v[0:1]
	v_mov_b64_e32 v[110:111], v[0:1]
	v_mov_b64_e32 v[120:121], v[0:1]
	v_mov_b64_e32 v[122:123], v[0:1]
	v_mov_b64_e32 v[124:125], v[0:1]
	v_mov_b64_e32 v[126:127], v[0:1]

.LBB0_1428:
	s_ashr_i32 s45, s44, 31
	s_lshl_b64 s[46:47], s[44:45], 20
	s_add_u32 s46, s2, s46
	s_addc_u32 s47, s3, s47
	s_and_b64 s[48:49], s[8:9], exec
	s_cselect_b32 s45, s47, s55
	s_cselect_b32 s51, s46, s54
	s_ashr_i32 s43, s42, 31
	s_lshl_b64 s[48:49], s[42:43], 20
	s_add_u32 s48, s18, s48
	s_addc_u32 s49, s19, s49
	s_and_b64 s[58:59], s[8:9], exec
	s_cselect_b32 s43, s49, s57
	s_cselect_b32 s69, s48, s56
	s_add_u32 s70, s56, 0x100
	v_mov_b32_e32 v0, 0
	s_addc_u32 s71, s57, 0
	s_mov_b32 s72, -2
	s_waitcnt lgkmcnt(0)
	v_mov_b32_e32 v1, v0
	v_mov_b64_e32 v[2:3], v[0:1]
	v_mov_b64_e32 v[4:5], v[0:1]
	v_mov_b64_e32 v[6:7], v[0:1]
	v_mov_b64_e32 v[16:17], v[0:1]
	v_mov_b64_e32 v[18:19], v[0:1]
	v_mov_b64_e32 v[20:21], v[0:1]
	v_mov_b64_e32 v[22:23], v[0:1]
	v_mov_b64_e32 v[32:33], v[0:1]
	v_mov_b64_e32 v[34:35], v[0:1]
	v_mov_b64_e32 v[36:37], v[0:1]
	v_mov_b64_e32 v[38:39], v[0:1]
	v_mov_b64_e32 v[48:49], v[0:1]
	v_mov_b64_e32 v[50:51], v[0:1]
	v_mov_b64_e32 v[52:53], v[0:1]
	v_mov_b64_e32 v[54:55], v[0:1]
	v_mov_b64_e32 v[8:9], v[0:1]
	v_mov_b64_e32 v[10:11], v[0:1]
	v_mov_b64_e32 v[12:13], v[0:1]
	v_mov_b64_e32 v[14:15], v[0:1]
	v_mov_b64_e32 v[24:25], v[0:1]
	v_mov_b64_e32 v[26:27], v[0:1]
	v_mov_b64_e32 v[28:29], v[0:1]
	v_mov_b64_e32 v[30:31], v[0:1]
	v_mov_b64_e32 v[40:41], v[0:1]
	v_mov_b64_e32 v[42:43], v[0:1]
	v_mov_b64_e32 v[44:45], v[0:1]
	v_mov_b64_e32 v[46:47], v[0:1]
	v_mov_b64_e32 v[56:57], v[0:1]
	v_mov_b64_e32 v[58:59], v[0:1]
	v_mov_b64_e32 v[60:61], v[0:1]
	v_mov_b64_e32 v[62:63], v[0:1]
	v_mov_b64_e32 v[64:65], v[0:1]
	v_mov_b64_e32 v[66:67], v[0:1]
	v_mov_b64_e32 v[68:69], v[0:1]
	v_mov_b64_e32 v[70:71], v[0:1]
	v_mov_b64_e32 v[80:81], v[0:1]
	v_mov_b64_e32 v[82:83], v[0:1]
	v_mov_b64_e32 v[84:85], v[0:1]
	v_mov_b64_e32 v[86:87], v[0:1]
	v_mov_b64_e32 v[96:97], v[0:1]
	v_mov_b64_e32 v[98:99], v[0:1]
	v_mov_b64_e32 v[100:101], v[0:1]
	v_mov_b64_e32 v[102:103], v[0:1]
	v_mov_b64_e32 v[112:113], v[0:1]
	v_mov_b64_e32 v[114:115], v[0:1]
	v_mov_b64_e32 v[116:117], v[0:1]
	v_mov_b64_e32 v[118:119], v[0:1]
	v_mov_b64_e32 v[72:73], v[0:1]
	v_mov_b64_e32 v[74:75], v[0:1]
	v_mov_b64_e32 v[76:77], v[0:1]
	v_mov_b64_e32 v[78:79], v[0:1]
	v_mov_b64_e32 v[88:89], v[0:1]
	v_mov_b64_e32 v[90:91], v[0:1]
	v_mov_b64_e32 v[92:93], v[0:1]
	v_mov_b64_e32 v[94:95], v[0:1]
	v_mov_b64_e32 v[104:105], v[0:1]
	v_mov_b64_e32 v[106:107], v[0:1]
	v_mov_b64_e32 v[108:109], v[0:1]
	v_mov_b64_e32 v[110:111], v[0:1]
	v_mov_b64_e32 v[120:121], v[0:1]
	v_mov_b64_e32 v[122:123], v[0:1]
	v_mov_b64_e32 v[124:125], v[0:1]
	v_mov_b64_e32 v[126:127], v[0:1]

.LBB0_1520:
	s_ashr_i32 s39, s38, 31
	s_lshl_b64 s[40:41], s[38:39], 20
	s_add_u32 s40, s3, s40
	s_addc_u32 s41, s18, s41
	s_and_b64 s[42:43], s[6:7], exec
	s_cselect_b32 s39, s41, s45
	s_cselect_b32 s63, s40, s44
	s_ashr_i32 s37, s36, 31
	s_lshl_b64 s[42:43], s[36:37], 20
	s_add_u32 s42, s19, s42
	s_addc_u32 s43, s21, s43
	s_and_b64 s[48:49], s[6:7], exec
	s_cselect_b32 s37, s43, s47
	s_cselect_b32 s64, s42, s46
	s_add_u32 s65, s46, 0x100
	v_mov_b32_e32 v0, 0
	s_addc_u32 s66, s47, 0
	s_mov_b32 s67, -2
	v_mov_b32_e32 v1, v0
	v_mov_b64_e32 v[2:3], v[0:1]
	v_mov_b64_e32 v[4:5], v[0:1]
	v_mov_b64_e32 v[6:7], v[0:1]
	v_mov_b64_e32 v[16:17], v[0:1]
	v_mov_b64_e32 v[18:19], v[0:1]
	v_mov_b64_e32 v[20:21], v[0:1]
	v_mov_b64_e32 v[22:23], v[0:1]
	v_mov_b64_e32 v[32:33], v[0:1]
	v_mov_b64_e32 v[34:35], v[0:1]
	v_mov_b64_e32 v[36:37], v[0:1]
	v_mov_b64_e32 v[38:39], v[0:1]
	v_mov_b64_e32 v[48:49], v[0:1]
	v_mov_b64_e32 v[50:51], v[0:1]
	v_mov_b64_e32 v[52:53], v[0:1]
	v_mov_b64_e32 v[54:55], v[0:1]
	v_mov_b64_e32 v[8:9], v[0:1]
	v_mov_b64_e32 v[10:11], v[0:1]
	v_mov_b64_e32 v[12:13], v[0:1]
	v_mov_b64_e32 v[14:15], v[0:1]
	v_mov_b64_e32 v[24:25], v[0:1]
	v_mov_b64_e32 v[26:27], v[0:1]
	v_mov_b64_e32 v[28:29], v[0:1]
	v_mov_b64_e32 v[30:31], v[0:1]
	v_mov_b64_e32 v[40:41], v[0:1]
	v_mov_b64_e32 v[42:43], v[0:1]
	v_mov_b64_e32 v[44:45], v[0:1]
	v_mov_b64_e32 v[46:47], v[0:1]
	v_mov_b64_e32 v[56:57], v[0:1]
	v_mov_b64_e32 v[58:59], v[0:1]
	v_mov_b64_e32 v[60:61], v[0:1]
	v_mov_b64_e32 v[62:63], v[0:1]
	v_mov_b64_e32 v[64:65], v[0:1]
	v_mov_b64_e32 v[66:67], v[0:1]
	v_mov_b64_e32 v[68:69], v[0:1]
	v_mov_b64_e32 v[70:71], v[0:1]
	v_mov_b64_e32 v[80:81], v[0:1]
	v_mov_b64_e32 v[82:83], v[0:1]
	v_mov_b64_e32 v[84:85], v[0:1]
	v_mov_b64_e32 v[86:87], v[0:1]
	v_mov_b64_e32 v[96:97], v[0:1]
	v_mov_b64_e32 v[98:99], v[0:1]
	v_mov_b64_e32 v[100:101], v[0:1]
	v_mov_b64_e32 v[102:103], v[0:1]
	v_mov_b64_e32 v[112:113], v[0:1]
	v_mov_b64_e32 v[114:115], v[0:1]
	v_mov_b64_e32 v[116:117], v[0:1]
	v_mov_b64_e32 v[118:119], v[0:1]
	v_mov_b64_e32 v[72:73], v[0:1]
	v_mov_b64_e32 v[74:75], v[0:1]
	v_mov_b64_e32 v[76:77], v[0:1]
	v_mov_b64_e32 v[78:79], v[0:1]
	v_mov_b64_e32 v[88:89], v[0:1]
	v_mov_b64_e32 v[90:91], v[0:1]
	v_mov_b64_e32 v[92:93], v[0:1]
	v_mov_b64_e32 v[94:95], v[0:1]
	v_mov_b64_e32 v[104:105], v[0:1]
	v_mov_b64_e32 v[106:107], v[0:1]
	v_mov_b64_e32 v[108:109], v[0:1]
	v_mov_b64_e32 v[110:111], v[0:1]
	v_mov_b64_e32 v[120:121], v[0:1]
	v_mov_b64_e32 v[122:123], v[0:1]
	v_mov_b64_e32 v[124:125], v[0:1]
	v_mov_b64_e32 v[126:127], v[0:1]

.LBB0_1598:
	s_ashr_i32 s39, s38, 31
	s_lshl_b64 s[40:41], s[38:39], 22
	s_add_u32 s40, s2, s40
	s_addc_u32 s41, s3, s41
	s_and_b64 s[42:43], s[6:7], exec
	s_cselect_b32 s39, s41, s49
	s_cselect_b32 s45, s40, s48
	s_ashr_i32 s37, s36, 31
	s_lshl_b64 s[42:43], s[36:37], 22
	s_add_u32 s42, s18, s42
	s_addc_u32 s43, s19, s43
	s_and_b64 s[52:53], s[6:7], exec
	s_cselect_b32 s37, s43, s51
	s_cselect_b32 s65, s42, s50
	s_add_u32 s66, s50, 0x100
	v_mov_b32_e32 v0, 0
	s_addc_u32 s67, s51, 0
	s_mov_b32 s68, -2
	s_waitcnt lgkmcnt(0)
	v_mov_b32_e32 v1, v0
	v_mov_b64_e32 v[2:3], v[0:1]
	v_mov_b64_e32 v[4:5], v[0:1]
	v_mov_b64_e32 v[6:7], v[0:1]
	v_mov_b64_e32 v[16:17], v[0:1]
	v_mov_b64_e32 v[18:19], v[0:1]
	v_mov_b64_e32 v[20:21], v[0:1]
	v_mov_b64_e32 v[22:23], v[0:1]
	v_mov_b64_e32 v[32:33], v[0:1]
	v_mov_b64_e32 v[34:35], v[0:1]
	v_mov_b64_e32 v[36:37], v[0:1]
	v_mov_b64_e32 v[38:39], v[0:1]
	v_mov_b64_e32 v[48:49], v[0:1]
	v_mov_b64_e32 v[50:51], v[0:1]
	v_mov_b64_e32 v[52:53], v[0:1]
	v_mov_b64_e32 v[54:55], v[0:1]
	v_mov_b64_e32 v[8:9], v[0:1]
	v_mov_b64_e32 v[10:11], v[0:1]
	v_mov_b64_e32 v[12:13], v[0:1]
	v_mov_b64_e32 v[14:15], v[0:1]
	v_mov_b64_e32 v[24:25], v[0:1]
	v_mov_b64_e32 v[26:27], v[0:1]
	v_mov_b64_e32 v[28:29], v[0:1]
	v_mov_b64_e32 v[30:31], v[0:1]
	v_mov_b64_e32 v[40:41], v[0:1]
	v_mov_b64_e32 v[42:43], v[0:1]
	v_mov_b64_e32 v[44:45], v[0:1]
	v_mov_b64_e32 v[46:47], v[0:1]
	v_mov_b64_e32 v[56:57], v[0:1]
	v_mov_b64_e32 v[58:59], v[0:1]
	v_mov_b64_e32 v[60:61], v[0:1]
	v_mov_b64_e32 v[62:63], v[0:1]
	v_mov_b64_e32 v[64:65], v[0:1]
	v_mov_b64_e32 v[66:67], v[0:1]
	v_mov_b64_e32 v[68:69], v[0:1]
	v_mov_b64_e32 v[70:71], v[0:1]
	v_mov_b64_e32 v[80:81], v[0:1]
	v_mov_b64_e32 v[82:83], v[0:1]
	v_mov_b64_e32 v[84:85], v[0:1]
	v_mov_b64_e32 v[86:87], v[0:1]
	v_mov_b64_e32 v[96:97], v[0:1]
	v_mov_b64_e32 v[98:99], v[0:1]
	v_mov_b64_e32 v[100:101], v[0:1]
	v_mov_b64_e32 v[102:103], v[0:1]
	v_mov_b64_e32 v[112:113], v[0:1]
	v_mov_b64_e32 v[114:115], v[0:1]
	v_mov_b64_e32 v[116:117], v[0:1]
	v_mov_b64_e32 v[118:119], v[0:1]
	v_mov_b64_e32 v[72:73], v[0:1]
	v_mov_b64_e32 v[74:75], v[0:1]
	v_mov_b64_e32 v[76:77], v[0:1]
	v_mov_b64_e32 v[78:79], v[0:1]
	v_mov_b64_e32 v[88:89], v[0:1]
	v_mov_b64_e32 v[90:91], v[0:1]
	v_mov_b64_e32 v[92:93], v[0:1]
	v_mov_b64_e32 v[94:95], v[0:1]
	v_mov_b64_e32 v[104:105], v[0:1]
	v_mov_b64_e32 v[106:107], v[0:1]
	v_mov_b64_e32 v[108:109], v[0:1]
	v_mov_b64_e32 v[110:111], v[0:1]
	v_mov_b64_e32 v[120:121], v[0:1]
	v_mov_b64_e32 v[122:123], v[0:1]
	v_mov_b64_e32 v[124:125], v[0:1]
	v_mov_b64_e32 v[126:127], v[0:1]
